# work-queue pop: thread 0 issues the next unit's claim at the start of the current unit's epilogue, the loop top only waits for it (same queue order, same number of claims)
# baseline (speedup 1.0000x reference)
; #define LAS __attribute__((address_space(3)))
; __device__ __forceinline__ void attn_phase(Frame& F, int layer, int rep) {
;     AttnP A; A.P = F.P; A.mixed = F.mix; A.cumloc = F.cumloc; A.cumtot = F.cumtot; A.subg = F.subln_g + layer * 512; A.nrm = F.ctl + 128 + layer * 128; A.mixm = F.mixm;
;     A.lam = F.lam[layer]; A.one_m_li = 1.0f - (0.8f - 0.6f * expf(-0.3f * (float)layer));
;     LAS int* cur = (LAS int*)(F.lds + LDS_MISC);
;     unsigned* counter = F.ctl + 16 * (layer + 1) + 4 * rep;
;     for (;;) {
;         if (F.tid == 0) *cur = (int)atomicAdd(counter, 1u);
;         __syncthreads();
;         const int idx = *cur;
;         __syncthreads();
;         if (idx >= N_UNITS) break;
.LBB0_435:
	s_andn2_b64 vcc, exec, s[0:1]
	s_cbranch_vccnz .LBB0_575
	v_mov_b32_e32 v0, v200
	s_load_dwordx2 s[16:17], s[86:87], 0x48
	s_load_dwordx2 s[36:37], s[86:87], 0x68
	s_lshl_b32 s34, s30, 9
	s_lshl_b32 s0, s30, 7
	s_lshl_b32 s22, s30, 4
	v_writelane_b32 v255, s88, 40
	s_waitcnt lgkmcnt(0)
	s_add_u32 s56, s36, 0x2000
	s_addc_u32 s57, s37, 0
	s_add_u32 s52, s36, 0x80000
	s_addc_u32 s53, s37, 0
	s_add_u32 s54, s36, 0x100000
	s_addc_u32 s55, s37, 0
	s_add_u32 s86, s36, 0x3b00000
	s_addc_u32 s87, s37, 0
	s_add_u32 s58, s36, 0x5c00000
	s_addc_u32 s59, s37, 0
	s_add_u32 s60, s36, 0x220000
	s_addc_u32 s61, s37, 0
	s_lshl_b64 s[24:25], s[34:35], 2
	v_writelane_b32 v255, s89, 41
	s_mov_b32 s1, s35
	s_add_u32 s88, s16, s24
	s_addc_u32 s89, s17, s25
	s_lshl_b64 s[0:1], s[0:1], 2
	s_mov_b32 s31, s35
	s_add_u32 s62, s36, s0
	s_addc_u32 s63, s37, s1
	s_lshl_b64 s[0:1], s[30:31], 2
	s_add_u32 s0, s36, s0
	s_addc_u32 s1, s37, s1
	v_mov_b32_e32 v2, 0x1000
	global_load_dword v181, v2, s[0:1]
	v_cvt_f32_u32_e32 v2, s30
	s_mov_b32 s0, 0x3fb8aa3b
	s_mov_b32 s23, s35
	v_cmp_eq_u32_e64 s[42:43], 0, v0
	v_mul_f32_e32 v2, 0xbe99999a, v2
	v_mul_f32_e32 v3, 0x3fb8aa3b, v2
	v_fma_f32 v4, v2, s0, -v3
	v_rndne_f32_e32 v5, v3
	v_fmac_f32_e32 v4, 0x32a5705f, v2
	v_sub_f32_e32 v3, v3, v5
	v_add_f32_e32 v3, v3, v4
	v_exp_f32_e32 v3, v3
	v_cvt_i32_f32_e32 v4, v5
	s_mov_b32 s0, 0xc2ce8ed0
	v_cmp_ngt_f32_e32 vcc, s0, v2
	s_mov_b32 s0, 0x42b17218
	v_ldexp_f32 v3, v3, v4
	v_cndmask_b32_e32 v3, 0, v3, vcc
	v_cmp_nlt_f32_e32 vcc, s0, v2
	s_lshl_b64 s[0:1], s[22:23], 2
	s_add_u32 s68, s36, s0
	v_cndmask_b32_e32 v2, v217, v3, vcc
	v_mov_b32_e32 v3, 0xbf4ccccd
	v_fmamk_f32 v2, v2, 0x3f19999a, v3
	v_add_f32_e32 v224, 1.0, v2
	s_addc_u32 s69, s37, s1
	s_mov_b32 s32, 0
	s_branch .LBB0_441
.Lpop_early:
	s_mov_b32 s32, 0
	s_waitcnt vmcnt(0)
	v_readfirstlane_b32 s16, v253
	v_mov_b32_e32 v0, 0
	s_branch .Lpop_join

; __device__ __forceinline__ void attn_phase(Frame& F, int layer, int rep) {
;     ...
;     for (;;) {
;         if (F.tid == 0) *cur = (int)atomicAdd(counter, 1u);
;         __syncthreads();
;         const int idx = *cur;
.LBB0_441:
	s_and_saveexec_b64 s[0:1], s[42:43]
	s_cbranch_execz .LBB0_445
	s_cmp_eq_u32 s32, 1
	s_cbranch_scc1 .Lpop_early
	s_mov_b64 s[22:23], exec
	v_mbcnt_lo_u32_b32 v0, s22, 0
	v_mbcnt_hi_u32_b32 v0, s23, v0
	v_cmp_eq_u32_e32 vcc, 0, v0
	s_and_saveexec_b64 s[16:17], vcc
	s_cbranch_execz .LBB0_444
	s_bcnt1_i32_b64 s22, s[22:23]
	v_mov_b32_e32 v2, s22
	global_atomic_add v2, v1, v2, s[68:69] offset:64 sc0

; __device__ __forceinline__ void attn_phase(Frame& F, int layer, int rep) {
;     ...
;         if (F.tid == 0) *cur = (int)atomicAdd(counter, 1u);
;         __syncthreads();
;         const int idx = *cur;
.Lpop_join:
	v_mov_b32_e32 v2, s80
	s_nop 0
	v_add_u32_e32 v0, s16, v0
	ds_write_b32 v2, v0

; __device__ __forceinline__ float swap32_sum(float m) { auto rr = __builtin_amdgcn_permlane32_swap(__float_as_uint(m), __float_as_uint(m), false, false); return __uint_as_float(rr[0]) + __uint_as_float(rr[1]); }
; template <bool DIFF>
; __device__ __forceinline__ void attn_unit(const AttnP& A, int b, int h, int qi, ldsp lds) {
;     ...
;     const float lt = swap32_sum(l_run);
;     const float inv = lt > 0.f ? 1.0f / lt : 0.f;
; __device__ __forceinline__ void attn_phase(Frame& F, int layer, int rep) {
;     ...
;     for (;;) {
;         if (F.tid == 0) *cur = (int)atomicAdd(counter, 1u);
.LBB0_488:
	s_and_saveexec_b64 s[0:1], s[42:43]
	v_mov_b32_e32 v253, 1
	global_atomic_add v253, v1, v253, s[68:69] offset:64 sc0
	s_mov_b64 exec, s[0:1]
	s_mov_b32 s32, 1
	v_mov_b32_e32 v38, v154
	s_nop 1
	v_permlane32_swap_b32_e32 v154, v38
	s_mov_b64 s[0:1], -1
	s_and_b64 vcc, exec, s[70:71]
	s_cbranch_vccz .LBB0_490
	v_lshlrev_b32_e32 v0, 11, v146
	v_and_b32_e32 v0, 0x7800, v0
	v_lshl_add_u64 v[36:37], s[60:61], 0, v[0:1]
	s_mov_b64 s[0:1], 0

; __device__ __forceinline__ float swap32_sum(float m) { auto rr = __builtin_amdgcn_permlane32_swap(__float_as_uint(m), __float_as_uint(m), false, false); return __uint_as_float(rr[0]) + __uint_as_float(rr[1]); }
; template <bool DIFF>
; __device__ __forceinline__ void attn_unit(const AttnP& A, int b, int h, int qi, ldsp lds) {
;     ...
;     const float lt = swap32_sum(l_run);
;     const float inv = lt > 0.f ? 1.0f / lt : 0.f;
; __device__ __forceinline__ void attn_phase(Frame& F, int layer, int rep) {
;     ...
;     for (;;) {
;         if (F.tid == 0) *cur = (int)atomicAdd(counter, 1u);
.LBB0_515:
	s_and_saveexec_b64 s[0:1], s[42:43]
	v_mov_b32_e32 v253, 1
	global_atomic_add v253, v1, v253, s[68:69] offset:64 sc0
	s_mov_b64 exec, s[0:1]
	s_mov_b32 s32, 1
	v_mov_b32_e32 v67, v230
	v_and_b32_e32 v66, 63, v225
	s_ashr_i32 s23, s22, 31
	v_permlane32_swap_b32_e32 v230, v67
	s_mov_b64 s[0:1], -1
	s_and_b64 vcc, exec, s[24:25]
	s_cbranch_vccz .LBB0_517
	v_lshlrev_b32_e32 v0, 11, v192
	v_and_b32_e32 v0, 0x7800, v0
	v_lshl_add_u64 v[76:77], s[60:61], 0, v[0:1]
	s_mov_b64 s[0:1], 0
